# conversion engine (v7 form) carrying only the P0 share (w_up + w_gate tail); P4 keeps its embedded conversion
# baseline (speedup 1.0000x reference)
; __global__ void __launch_bounds__(NWAVES * 64, 2) fwd(Args args) {
;     ...
;         if (embed) {
;             p0_transpose_matrix(w_gate + (size_t)(32 * CV_GATE_KB) * DFF, D - 32 * CV_GATE_KB, DFF, WguT + 32 * CV_GATE_KB, D, 1, scr, gw, NGW, F.lane, g_ffn + 32 * CV_GATE_KB);
;         } else {
;             p0_transpose_matrix(w_up_pool, PW, D, WupT, D, 0, scr, gw, NGW, F.lane);
;             p0_transpose_matrix(w_up_hgrn, HW, D, WupT + PW, D, 0, scr, gw, NGW, F.lane);
;             p0_transpose_matrix(w_out, D, D, WoT, D, 0, scr, gw, NGW, F.lane);
;             p0_transpose_matrix(w_gate, D, DFF, WguT, D, 1, scr, gw, NGW, F.lane, g_ffn);
;         }
;         p0_transpose_matrix(w_up, D, DFF, WguT, D, 2, scr, gw, NGW, F.lane, g_ffn);
.LBB0_143:
	s_add_i32 s32, s32, 1
	s_mov_b32 s97, 0
	s_cmp_lt_i32 s32, 1
	s_cbranch_scc1 .Leng_done
	s_sub_i32 s93, s32, 1
	s_and_b32 s93, s93, 3
	s_cmp_lg_u32 s93, 0
	s_cbranch_scc1 .Leng_not0
	s_mov_b64 s[100:101], 0
	s_bitcmp1_b32 s85, 31
	s_cbranch_scc1 .Leng_grpB
	s_lshr_b32 s93, s85, 16
	s_cmp_ge_u32 s93, 0xa2
	s_cbranch_scc1 .Leng_done
	s_cmp_lt_u32 s93, 0x80
	s_cbranch_scc0 .Leng_gate
	v_readlane_b32 s98, v245, 2
	v_readlane_b32 s99, v245, 3
	s_movk_i32 s100, 0x80
	s_branch .Leng_mat
